# one static s_setprio 1 for waves 0-3 at kernel entry (per-block flips already removed)
# baseline (speedup 1.0000x reference)
.LBB0_8:
	s_lshr_b32 s80, s1, 6
	s_cmp_lt_u32 s80, 4
	s_cbranch_scc0 .Lmy_prio_done
	s_setprio 1
.Lmy_prio_done:
	v_writelane_b32 v250, s91, 7
	s_andn2_b64 vcc, exec, s[4:5]
	v_writelane_b32 v250, s80, 8
	s_cbranch_vccnz .LBB0_49
	s_mov_b32 s2, s80
	s_mov_b32 s3, -1
	s_lshl_b32 s2, s2, 6
	v_mbcnt_lo_u32_b32 v0, s3, 0
	v_mbcnt_hi_u32_b32 v0, s3, v0
	s_lshl_b32 s3, s91, 9
	s_add_i32 s2, s2, s3
	s_mov_b64 s[16:17], 0x2000000
	v_add_u32_e32 v32, s2, v0
	v_ashrrev_i32_e32 v33, 31, v32
	v_lshlrev_b64 v[38:39], 3, v[32:33]
	v_writelane_b32 v250, s3, 6
	s_lshl_b32 s92, s94, 9
	s_mov_b64 s[4:5], s[96:97]
	s_mov_b64 s[6:7], s[96:97]
	s_mov_b64 s[8:9], s[96:97]
	v_cmp_gt_u64_e32 vcc, s[16:17], v[38:39]
	s_and_saveexec_b64 s[18:19], vcc
	s_cbranch_execz .LBB0_37
	s_load_dwordx2 s[2:3], s[6:7], 0x110
	s_load_dwordx2 s[10:11], s[8:9], 0x110
	s_load_dwordx2 s[12:13], s[4:5], 0x0
	v_lshlrev_b64 v[0:1], 5, v[32:33]
	s_mov_b64 s[20:21], 0
	s_waitcnt lgkmcnt(0)
	s_add_u32 s22, s2, 0x1ab00000
	s_addc_u32 s23, s3, 0
	s_add_u32 s24, s10, 0x4eb00000
	s_addc_u32 s25, s11, 0
	s_ashr_i32 s93, s92, 31
	s_lshl_b64 s[26:27], s[92:93], 3
	s_cmp_lg_u64 s[2:3], 0
	s_cselect_b64 s[28:29], -1, 0
	s_cmp_lg_u64 s[10:11], 0
	s_cselect_b64 s[30:31], -1, 0
	s_lshl_b64 s[34:35], s[92:93], 5
	s_lshl_b64 s[36:37], s[92:93], 7
	s_lshl_b64 s[38:39], s[92:93], 4
	s_add_u32 s4, s2, s38
	s_addc_u32 s5, s3, s39
	s_add_u32 s40, s4, 0x1ab00000
	s_addc_u32 s41, s5, 0
	s_lshl_b64 s[42:43], s[92:93], 6
	s_add_u32 s4, s10, s38
	s_addc_u32 s5, s11, s39
	s_add_u32 s44, s4, 0x4eb00000
	s_addc_u32 s45, s5, 0
	s_or_b32 s46, s42, 16
	s_add_u32 s4, s2, s34
	s_addc_u32 s5, s3, s35
	s_add_u32 s48, s4, 0x1ab00000
	s_addc_u32 s49, s5, 0
	s_add_u32 s4, s10, s34
	s_addc_u32 s5, s11, s35
	s_add_u32 s50, s4, 0x4eb00000
	s_mul_i32 s4, s92, 0x60
	s_addc_u32 s51, s5, 0
	s_or_b32 s54, s4, 16
	s_mul_i32 s5, s92, 48
	s_mul_hi_i32 s4, s92, 48
	s_add_u32 s2, s2, s5
	s_addc_u32 s3, s3, s4
	s_add_u32 s56, s2, 0x1ab00000
	s_addc_u32 s57, s3, 0
	s_add_u32 s2, s10, s5
	s_addc_u32 s3, s11, s4
	v_lshl_add_u64 v[34:35], s[12:13], 0, v[0:1]
	s_add_u32 s58, s2, 0x4eb00000
	v_mov_b32_e32 v0, 0
	v_lshlrev_b64 v[36:37], 4, v[32:33]
	s_mov_b32 s47, s43
	s_mul_hi_i32 s53, s92, 24
	s_mul_i32 s52, s92, 24
	s_mul_hi_i32 s55, s92, 0x60
	s_addc_u32 s59, s3, 0
	s_mov_b64 s[60:61], 0x1ffffff
	v_mov_b32_e32 v1, v0
	v_mov_b32_e32 v2, v0
	v_mov_b32_e32 v3, v0
	v_mov_b32_e32 v4, v0
	v_mov_b32_e32 v5, v0
	v_mov_b32_e32 v6, v0
	v_mov_b32_e32 v7, v0
	v_mov_b32_e32 v12, v0
	v_mov_b32_e32 v13, v0
	v_mov_b32_e32 v14, v0
	v_mov_b32_e32 v15, v0
	v_mov_b32_e32 v8, v0
	v_mov_b32_e32 v9, v0
	v_mov_b32_e32 v10, v0
	v_mov_b32_e32 v11, v0
	v_mov_b32_e32 v16, v0
	v_mov_b32_e32 v17, v0
	v_mov_b32_e32 v18, v0
	v_mov_b32_e32 v19, v0
	v_mov_b32_e32 v20, v0
	v_mov_b32_e32 v21, v0
	v_mov_b32_e32 v22, v0
	v_mov_b32_e32 v23, v0
	s_branch .LBB0_12
